# v70: v68 + the L1 invalidate of an invalidating seam is issued after the arrival store instead of before it
# baseline (speedup 1.0000x reference)
.LBB0_415:
	s_getreg_b32 s2, hwreg(HW_REG_XCC_ID, 0, 4)
	s_waitcnt vmcnt(0)
	s_waitcnt lgkmcnt(0)
	s_barrier
	s_and_saveexec_b64 s[0:1], s[14:15]
	s_cbranch_execz .LBB0_467
	v_readlane_b32 s98, v255, 63
	s_nop 0
	s_cmp_lg_u32 s98, 0
	s_cbranch_scc1 .Lhb_full_g1
	s_cmp_lg_u32 s33, 64
	s_cbranch_scc1 .Lhb_full_g1
	v_readlane_b32 s98, v255, 56
	v_readlane_b32 s100, v253, 1
	v_readlane_b32 s101, v253, 2
	v_readlane_b32 s99, v253, 0
	v_readlane_b32 vcc_lo, v254, 28
	s_add_i32 s98, s98, 1
	v_writelane_b32 v255, s98, 56
	s_lshl_b32 s99, s99, 14
	s_sub_u32 s100, s100, s99
	s_subb_u32 s101, s101, 0
	s_add_u32 s100, s100, 0xb000
	s_addc_u32 s101, s101, 0
	s_getreg_b32 s99, hwreg(HW_REG_XCC_ID, 0, 4)
	s_and_b32 s99, s99, 15
	s_lshl_b32 s99, s99, 8
	s_lshl_b32 vcc_hi, vcc_lo, 2
	s_add_i32 vcc_hi, vcc_hi, s99
	v_mov_b32_e32 v4, vcc_hi
	v_mov_b32_e32 v5, s98
	global_store_dword v4, v5, s[100:101]
	buffer_inv sc1
	s_cmp_eq_u32 vcc_lo, 0
	s_cbranch_scc1 .Lhb_lead_g1
	s_lshr_b32 s99, s99, 2
	v_mov_b32_e32 v4, s99
	s_mov_b32 s99, 0

.LBB0_642:
	s_getreg_b32 s4, hwreg(HW_REG_XCC_ID, 0, 4)
	s_waitcnt vmcnt(0)
	s_barrier
	s_and_saveexec_b64 s[2:3], s[14:15]
	s_cbranch_execz .LBB0_694
	v_readlane_b32 s98, v255, 63
	s_nop 0
	s_cmp_lg_u32 s98, 0
	s_cbranch_scc1 .Llb_full_g2
	s_cmp_lg_u32 s33, 64
	s_cbranch_scc1 .Llb_full_g2
	v_readlane_b32 s98, v255, 56
	v_readlane_b32 s100, v253, 1
	v_readlane_b32 s101, v253, 2
	v_readlane_b32 s99, v253, 0
	v_readlane_b32 vcc_lo, v254, 28
	s_add_i32 s98, s98, 1
	v_writelane_b32 v255, s98, 56
	s_lshl_b32 s99, s99, 14
	s_sub_u32 s100, s100, s99
	s_subb_u32 s101, s101, 0
	s_add_u32 s100, s100, 0xb000
	s_addc_u32 s101, s101, 0
	s_getreg_b32 s99, hwreg(HW_REG_XCC_ID, 0, 4)
	s_and_b32 s99, s99, 15
	s_lshl_b32 s99, s99, 8
	s_lshl_b32 vcc_hi, vcc_lo, 2
	s_add_i32 vcc_hi, vcc_hi, s99
	v_mov_b32_e32 v4, vcc_hi
	v_mov_b32_e32 v5, s98
	global_store_dword v4, v5, s[100:101]
	buffer_inv sc1
	s_branch .Llb_lead_g2
	s_lshr_b32 s99, s99, 2
	v_mov_b32_e32 v4, s99
	s_mov_b32 s99, 0

.LBB0_780:
	s_getreg_b32 s2, hwreg(HW_REG_XCC_ID, 0, 4)
	s_waitcnt vmcnt(0)
	s_barrier
	s_and_saveexec_b64 s[0:1], s[14:15]
	s_cbranch_execz .LBB0_832
	v_readlane_b32 s98, v255, 63
	s_nop 0
	s_cmp_lg_u32 s98, 0
	s_cbranch_scc1 .Llb_full_g3
	s_cmp_lg_u32 s33, 64
	s_cbranch_scc1 .Llb_full_g3
	v_readlane_b32 s98, v255, 56
	v_readlane_b32 s100, v253, 1
	v_readlane_b32 s101, v253, 2
	v_readlane_b32 s99, v253, 0
	v_readlane_b32 vcc_lo, v254, 28
	s_add_i32 s98, s98, 1
	v_writelane_b32 v255, s98, 56
	s_lshl_b32 s99, s99, 14
	s_sub_u32 s100, s100, s99
	s_subb_u32 s101, s101, 0
	s_add_u32 s100, s100, 0xb000
	s_addc_u32 s101, s101, 0
	s_getreg_b32 s99, hwreg(HW_REG_XCC_ID, 0, 4)
	s_and_b32 s99, s99, 15
	s_lshl_b32 s99, s99, 8
	s_lshl_b32 vcc_hi, vcc_lo, 2
	s_add_i32 vcc_hi, vcc_hi, s99
	v_mov_b32_e32 v4, vcc_hi
	v_mov_b32_e32 v5, s98
	global_store_dword v4, v5, s[100:101]
	buffer_inv sc1
	s_branch .Llb_lead_g3
	s_lshr_b32 s99, s99, 2
	v_mov_b32_e32 v4, s99
	s_mov_b32 s99, 0
